# stack: attention MFMA-only M section (compare, K-address adds, tail bookkeeping moved out) + GEMM pure-MFMA segments
# speedup vs baseline: 1.0085x; 1.0041x over previous
.LBB0_405:
	s_barrier
	s_add_i32 s18, s38, 0x4000
	s_cmpk_lg_u32 s38, 0x8000
	s_cselect_b32 s38, s18, 0
	s_mov_b64 s[66:67], -1
	s_and_b64 vcc, exec, s[48:49]
	s_cbranch_vccz .LBB0_409
	s_cmpk_gt_u32 s22, 0x7c
	s_cbranch_scc1 .LBB0_408
	s_add_u32 s36, s64, s62
	s_addc_u32 s37, s65, s63
	s_add_u32 s18, s36, 0x240000
	s_addc_u32 s19, s37, 0
	s_add_u32 s66, s36, 0x24c000
	s_addc_u32 s67, s37, 0
	s_add_u32 s68, s36, 0x258000
	s_addc_u32 s69, s37, 0
	s_add_u32 s36, s36, 0x264000
	s_addc_u32 s37, s37, 0
	s_add_i32 s39, s38, 0x4000
	s_cmpk_lg_u32 s38, 0x8000
	s_cselect_b32 s39, s39, 0
	s_add_i32 s39, s39, s75
	s_mov_b32 s78, m0
	s_add_u32 m0, s39, 0
	s_nop 0
	global_load_lds_dwordx4 v205, s[18:19]
	s_add_u32 m0, s39, 1024
	s_nop 0
	global_load_lds_dwordx4 v206, s[66:67]
	s_add_u32 m0, s39, 2048
	s_nop 0
	global_load_lds_dwordx4 v205, s[68:69]
	s_add_u32 m0, s39, 3072
	s_nop 0
	global_load_lds_dwordx4 v206, s[36:37]
	s_mov_b32 m0, s78

; __device__ __forceinline__ void attn_body(const bf16* __restrict__ Qb, const bf16* __restrict__ Kh, const bf16* __restrict__ Vh, float* __restrict__ Ob, int seq, LAS unsigned char* lds, const int wid, const bool fin) {
;     ...
;   for (int t = 0; t < NT; t += 2) { TILE(0, t); TILE(1, t + 1); }
.LBB0_425:
	s_barrier
	s_add_i32 s8, s38, 0x4000
	s_cmpk_lg_u32 s38, 0x8000
	s_cselect_b32 s38, s8, 0
	s_add_i32 s8, s22, 2
	v_add_f32_e32 v216, v216, v217
	s_add_u32 s64, s64, 0x180000
	v_fmac_f32_e32 v216, v0, v215
	v_add_f32_e32 v0, v219, v220
	s_addc_u32 s65, s65, 0
	v_fmac_f32_e32 v0, v216, v218
	s_cmpk_gt_u32 s22, 0x7d
	s_cbranch_scc1 .LBB0_433
	s_mov_b32 s22, s8
	s_mov_b64 s[8:9], -1
	s_and_b64 vcc, exec, s[48:49]
	s_cbranch_vccnz .LBB0_385
	s_branch .LBB0_388
